# attention K/V staging by LDS-DMA into a 3-deep LDS ring (2 tiles in flight, counted vmcnt, one barrier per tile) on top of ping-pong
# speedup vs baseline: 1.0109x; 1.0033x over previous
; #define GAS __attribute__((address_space(1)))
; #define LAS __attribute__((address_space(3)))
; DI void u_attn2(Frame& F, int h, int qb, int sp, int ntile) {
;     ...
;     unsigned char* ws = F.ws; const int tid = tid_, lane = tid & 63, w = F.wave, g4 = lane >> 4, lc = lane & 15;
;     LAS bf16* Ks = (LAS bf16*)F.lds; LAS bf16* Vs = Ks + 64 * 200;
;     const bf16* QM = (const bf16*)(ws + WS_QM); const bf16* KM = (const bf16*)(ws + WS_KM) + h * 192; const bf16* VT = (const bf16*)(ws + WS_VT) + (size_t)(h * 128) * S;
;     const int q0 = qb * 256 + w * 32, cw = 4 * qb + (w >> 1);
;     bf16x8 qf[2][6];
; #pragma unroll
;     for (int qq = 0; qq < 2; ++qq)
; #pragma unroll
;         for (int ks = 0; ks < 6; ++ks) qf[qq][ks] = *(const GAS bf16x8*)(QM + (size_t)(q0 + qq * 16 + lc) * 768 + h * 192 + ks * 32 + g4 * 8);
;     f32x4 o[8][2]; float mrun[2], lrun[2];
; #pragma unroll
;     for (int db = 0; db < 8; ++db)
; #pragma unroll
;         for (int qq = 0; qq < 2; ++qq) o[db][qq] = (f32x4){0.f, 0.f, 0.f, 0.f};
;     mrun[0] = mrun[1] = -1e30f; lrun[0] = lrun[1] = 0.f;
;     u32x4 kreg[3], vreg[2];
;     const int kt0 = 16 * sp;
;     ...
;     AT_LOAD(kt0)
.LBB0_2232:
	s_bitcmp0_b32 s44, 0
	s_cselect_b32 s31, s9, s41
	s_add_i32 s30, s31, s30
	s_cmpk_gt_i32 s30, 0x23f
	s_cbranch_scc1 .LBB0_2231
	s_ashr_i32 s31, s30, 31
	s_lshl_b64 s[30:31], s[30:31], 2
	s_add_u32 s30, s25, s30
	s_addc_u32 s31, s40, s31
	v_mov_b64_e32 v[2:3], s[30:31]
	flat_load_dword v138, v[2:3]
	v_mov_b32_e32 v158, v159
	v_mov_b32_e32 v20, v19
	v_mov_b32_e32 v21, v19
	v_mov_b32_e32 v18, v19
	v_mov_b64_e32 v[64:65], v[20:21]
	v_mov_b64_e32 v[56:57], v[20:21]
	v_mov_b64_e32 v[60:61], v[20:21]
	v_mov_b64_e32 v[68:69], v[20:21]
	v_mov_b64_e32 v[136:137], v[20:21]
	v_mov_b64_e32 v[120:121], v[20:21]
	v_mov_b64_e32 v[108:109], v[20:21]
	v_mov_b64_e32 v[104:105], v[20:21]
	v_mov_b64_e32 v[100:101], v[20:21]
	v_mov_b64_e32 v[96:97], v[20:21]
	v_mov_b64_e32 v[92:93], v[20:21]
	v_mov_b64_e32 v[88:89], v[20:21]
	v_mov_b64_e32 v[84:85], v[20:21]
	v_mov_b64_e32 v[80:81], v[20:21]
	v_mov_b64_e32 v[72:73], v[20:21]
	v_mov_b64_e32 v[76:77], v[20:21]
	v_bfe_u32 v2, v158, 4, 2
	s_mov_b32 s46, 0
	v_mov_b32_e32 v164, 0xf149f2ca
	v_mov_b32_e32 v165, 0
	v_mov_b32_e32 v163, 0
	v_mov_b32_e32 v162, 0xf149f2ca
	v_mov_b64_e32 v[62:63], v[18:19]
	v_mov_b64_e32 v[54:55], v[18:19]
	v_mov_b64_e32 v[58:59], v[18:19]
	v_mov_b64_e32 v[66:67], v[18:19]
	v_mov_b64_e32 v[134:135], v[18:19]
	v_mov_b64_e32 v[118:119], v[18:19]
	v_mov_b64_e32 v[106:107], v[18:19]
	v_mov_b64_e32 v[102:103], v[18:19]
	v_mov_b64_e32 v[98:99], v[18:19]
	v_mov_b64_e32 v[94:95], v[18:19]
	v_mov_b64_e32 v[90:91], v[18:19]
	v_mov_b64_e32 v[86:87], v[18:19]
	v_mov_b64_e32 v[82:83], v[18:19]
	v_mov_b64_e32 v[78:79], v[18:19]
	v_mov_b64_e32 v[70:71], v[18:19]
	v_and_b32_e32 v161, 15, v158
	v_lshlrev_b32_e32 v160, 3, v2
	v_mov_b64_e32 v[74:75], v[18:19]
	s_waitcnt vmcnt(0) lgkmcnt(0)
	v_ashrrev_i32_e32 v179, 12, v138
	v_and_b32_e32 v178, 3, v138
	v_bfe_u32 v177, v138, 2, 5
	v_bfe_u32 v176, v138, 7, 5
	v_cmp_lt_i32_e32 vcc, 0, v179
	s_and_saveexec_b64 s[30:31], vcc
	s_cbranch_execz .LBB0_2245
	v_mul_u32_u24_e32 v3, 0xc0, v178
	v_lshl_add_u32 v4, v177, 8, s42
	v_lshlrev_b32_e32 v18, 1, v3
	v_or_b32_e32 v30, v4, v161
	v_lshl_add_u64 v[4:5], s[12:13], 0, v[18:19]
	v_lshlrev_b32_e32 v2, 4, v2
	v_mov_b32_e32 v3, v19
	v_lshl_add_u64 v[20:21], v[4:5], 0, v[2:3]
	s_movk_i32 s38, 0x600
	v_mad_i64_i32 v[26:27], s[36:37], v30, s38, v[20:21]
	v_or_b32_e32 v30, 16, v30
	v_mad_i64_i32 v[20:21], s[36:37], v30, s38, v[20:21]
	s_mov_b32 s36, 0x2aaaaaab
	global_load_dwordx4 v[2:5], v[26:27], off
	global_load_dwordx4 v[6:9], v[26:27], off offset:64
	global_load_dwordx4 v[10:13], v[26:27], off offset:128
	global_load_dwordx4 v[14:17], v[26:27], off offset:192
	global_load_dwordx4 v[22:25], v[26:27], off offset:256
	s_nop 0
	global_load_dwordx4 v[26:29], v[26:27], off offset:320
	s_nop 0
	global_load_dwordx4 v[30:33], v[20:21], off
	global_load_dwordx4 v[34:37], v[20:21], off offset:64
	global_load_dwordx4 v[38:41], v[20:21], off offset:128
	global_load_dwordx4 v[42:45], v[20:21], off offset:192
	global_load_dwordx4 v[46:49], v[20:21], off offset:256
	global_load_dwordx4 v[50:53], v[20:21], off offset:320
	v_mul_hi_i32 v20, v158, s36
	v_lshrrev_b32_e32 v21, 31, v20
	v_ashrrev_i32_e32 v20, 2, v20
	v_add_u32_e32 v80, v20, v21
	v_add_u32_e32 v20, 0x200, v158
	v_mul_hi_i32 v21, v20, s36
	v_lshrrev_b32_e32 v54, 31, v21
	v_ashrrev_i32_e32 v21, 2, v21
	v_add_u32_e32 v81, v21, v54
	v_add_u32_e32 v54, 0x400, v158
	v_mul_hi_i32 v21, v54, s36
	v_lshrrev_b32_e32 v55, 31, v21
	v_ashrrev_i32_e32 v21, 2, v21
	v_add_u32_e32 v82, v21, v55
	s_movk_i32 s39, 0xffe8
	v_mad_u64_u32 v[54:55], s[36:37], v82, s39, v[54:55]
	v_lshlrev_b32_e32 v74, 21, v178
	v_mov_b32_e32 v75, v19
	v_ashrrev_i32_e32 v56, 3, v158
	v_ashrrev_i32_e32 v60, 3, v20
	v_lshl_add_u64 v[74:75], s[18:19], 0, v[74:75]
	v_lshlrev_b32_e32 v76, 11, v176
	v_mov_b32_e32 v77, v19
	v_lshlrev_b32_e32 v55, 4, v158
	v_ashrrev_i32_e32 v57, 31, v56
	v_ashrrev_i32_e32 v61, 31, v60
	v_mad_u64_u32 v[20:21], s[36:37], v81, s39, v[20:21]
	v_lshl_add_u64 v[74:75], v[74:75], 0, v[76:77]
	v_and_b32_e32 v76, 0x70, v55
	v_lshlrev_b64 v[58:59], 14, v[56:57]
	v_lshlrev_b64 v[62:63], 14, v[60:61]
	v_lshlrev_b32_e32 v64, 3, v54
	v_lshlrev_b32_e32 v21, 10, v176
	v_lshl_add_u64 v[74:75], v[74:75], 0, v[76:77]
	v_ashrrev_i32_e32 v65, 31, v64
	v_lshlrev_b32_e32 v66, 3, v20
	v_mad_u64_u32 v[68:69], s[36:37], v80, s39, v[158:159]
	v_lshl_add_u64 v[72:73], s[16:17], 0, v[18:19]
	v_lshl_add_u64 v[78:79], v[74:75], 0, v[62:63]
	v_lshl_add_u64 v[74:75], v[74:75], 0, v[58:59]
	v_add_u32_e32 v61, v82, v21
	v_ashrrev_i32_e32 v67, 31, v66
	v_mad_i64_i32 v[74:75], s[36:37], v61, s38, v[72:73]
	v_lshlrev_b64 v[64:65], 1, v[64:65]
	v_add_u32_e32 v69, v81, v21
	v_lshlrev_b32_e32 v70, 3, v68
	v_lshl_add_u64 v[74:75], v[74:75], 0, v[64:65]
	v_mad_i64_i32 v[78:79], s[36:37], v69, s38, v[72:73]
	v_lshlrev_b64 v[66:67], 1, v[66:67]
	v_ashrrev_i32_e32 v71, 31, v70
	v_lshl_add_u64 v[78:79], v[78:79], 0, v[66:67]
	v_add_u32_e32 v74, v21, v80
	v_mad_i64_i32 v[72:73], s[36:37], v74, s38, v[72:73]
	v_lshlrev_b64 v[70:71], 1, v[70:71]
	v_lshl_add_u64 v[72:73], v[72:73], 0, v[70:71]
	v_and_b32_e32 v21, 48, v158
	v_add_u32_e32 v73, s11, v21
	v_mov_b32_e32 v21, s11
	s_movk_i32 s36, 0x190
	v_mad_u32_u24 v77, v161, s90, v21
	v_mul_lo_u32 v21, v80, s36
	v_add_u32_e32 v79, s11, v21
	v_mul_lo_u32 v21, v81, s36
	v_lshlrev_b32_e32 v81, 4, v20
	v_mul_lo_u32 v20, v82, s36
	v_add_u32_e32 v82, s11, v20
	v_or_b32_e32 v20, 16, v161
	v_mul_u32_u24_e32 v86, 0x90, v20
	v_mov_b32_e32 v20, 0x3d000000
	v_add_u32_e32 v80, s11, v21
	v_mul_lo_u32 v84, v56, s90
	v_lshl_or_b32 v20, v178, 21, v20
	v_mov_b32_e32 v21, v19
	v_lshlrev_b32_e32 v56, 4, v138
; #define GAS __attribute__((address_space(1)))
; #define LAS __attribute__((address_space(3)))
; DI void u_attn2(Frame& F, int h, int qb, int sp, int ntile) {
;     int tid_ = F.tid; asm volatile("" : "+v"(tid_));
;     unsigned char* ws = F.ws; const int tid = tid_, lane = tid & 63, w = F.wave, g4 = lane >> 4, lc = lane & 15;
;     LAS bf16* Ks = (LAS bf16*)F.lds; LAS bf16* Vs = Ks + 64 * 200;
;     const bf16* QM = (const bf16*)(ws + WS_QM); const bf16* KM = (const bf16*)(ws + WS_KM) + h * 192; const bf16* VT = (const bf16*)(ws + WS_VT) + (size_t)(h * 128) * S;
;     const int q0 = qb * 256 + w * 32, cw = 4 * qb + (w >> 1);
;     bf16x8 qf[2][6];
; #pragma unroll
;     for (int qq = 0; qq < 2; ++qq)
; #pragma unroll
;         for (int ks = 0; ks < 6; ++ks) qf[qq][ks] = *(const GAS bf16x8*)(QM + (size_t)(q0 + qq * 16 + lc) * 768 + h * 192 + ks * 32 + g4 * 8);
;     f32x4 o[8][2]; float mrun[2], lrun[2];
; #pragma unroll
;     for (int db = 0; db < 8; ++db)
; #pragma unroll
;         for (int qq = 0; qq < 2; ++qq) o[db][qq] = (f32x4){0.f, 0.f, 0.f, 0.f};
;     mrun[0] = mrun[1] = -1e30f; lrun[0] = lrun[1] = 0.f;
;     u32x4 kreg[3], vreg[2];
;     const int kt0 = 16 * sp;
;     ...
;     AT_LOAD(kt0)
	v_lshlrev_b32_e32 v83, 4, v54
	v_lshl_add_u64 v[54:55], v[20:21], 0, v[62:63]
	v_and_b32_e32 v56, 0xf800, v56
	v_mov_b32_e32 v57, v19
	v_lshl_add_u64 v[20:21], v[20:21], 0, v[58:59]
	v_lshl_add_u64 v[168:169], v[20:21], 0, v[56:57]
	v_mad_i64_i32 v[20:21], s[36:37], v61, s38, v[64:65]
	v_lshl_add_u64 v[20:21], v[20:21], 0, v[18:19]
	s_mov_b64 s[48:49], 0x3c418000
	v_lshl_add_u64 v[170:171], v[20:21], 0, s[48:49]
	v_mad_i64_i32 v[20:21], s[36:37], v69, s38, v[66:67]
	v_lshl_add_u64 v[20:21], v[20:21], 0, v[18:19]
	v_lshl_add_u64 v[172:173], v[20:21], 0, s[48:49]
	v_mad_i64_i32 v[20:21], s[36:37], v74, s38, v[70:71]
	v_lshl_add_u64 v[20:21], v[20:21], 0, v[18:19]
	v_add_u32_e32 v72, s11, v76
	v_mul_u32_u24_e32 v75, 0x90, v161
	v_add_u32_e32 v78, s11, v160
	v_lshlrev_b32_e32 v68, 4, v68
	v_mul_lo_u32 v60, v60, s90
	v_mul_u32_u24_e32 v85, 0x190, v161
	v_lshl_add_u64 v[166:167], v[54:55], 0, v[56:57]
	v_lshl_add_u64 v[174:175], v[20:21], 0, s[48:49]
	v_mov_b32_e32 v20, v19
	v_mov_b32_e32 v21, v19
	v_or_b32_e32 v166, v166, v76
	v_or_b32_e32 v168, v168, v76
	v_mov_b32_e32 v18, v19
	v_add_u32_e32 v182, v79, v68
	v_add_u32_e32 v183, v80, v81
	v_add_u32_e32 v184, v82, v83
	v_add_u32_e32 v185, v72, v84
	v_add_u32_e32 v186, v72, v60
	v_add_u32_e32 v187, v73, v85
	v_add_u32_e32 v188, v77, v160
	v_add_u32_e32 v189, v78, v86
	v_add_u32_e32 v190, v78, v75
	v_mov_b64_e32 v[76:77], v[20:21]
	v_mov_b64_e32 v[72:73], v[20:21]
	v_mov_b64_e32 v[80:81], v[20:21]
	v_mov_b64_e32 v[84:85], v[20:21]
	v_mov_b64_e32 v[88:89], v[20:21]
	v_mov_b64_e32 v[92:93], v[20:21]
	v_mov_b64_e32 v[96:97], v[20:21]
	v_mov_b64_e32 v[100:101], v[20:21]
	v_mov_b64_e32 v[104:105], v[20:21]
	v_mov_b64_e32 v[108:109], v[20:21]
	v_mov_b64_e32 v[120:121], v[20:21]
	v_mov_b64_e32 v[136:137], v[20:21]
	v_mov_b64_e32 v[68:69], v[20:21]
	v_mov_b64_e32 v[60:61], v[20:21]
	v_mov_b64_e32 v[56:57], v[20:21]
	v_mov_b64_e32 v[64:65], v[20:21]
	v_lshl_add_u32 v180, v177, 2, s43
	v_lshlrev_b32_e32 v181, 4, v176
	v_mov_b32_e32 v163, 0
	v_mov_b32_e32 v162, 0xf149f2ca
	s_mov_b64 s[36:37], 0
	v_mov_b64_e32 v[74:75], v[18:19]
	v_mov_b64_e32 v[70:71], v[18:19]
	v_mov_b64_e32 v[78:79], v[18:19]
	v_mov_b64_e32 v[82:83], v[18:19]
	v_mov_b64_e32 v[86:87], v[18:19]
	v_mov_b64_e32 v[90:91], v[18:19]
	v_mov_b64_e32 v[94:95], v[18:19]
	v_mov_b64_e32 v[98:99], v[18:19]
	v_mov_b64_e32 v[102:103], v[18:19]
	v_mov_b64_e32 v[106:107], v[18:19]
	v_mov_b64_e32 v[118:119], v[18:19]
	v_mov_b64_e32 v[134:135], v[18:19]
	v_mov_b32_e32 v164, 0xf149f2ca
	v_mov_b32_e32 v165, 0
	v_mov_b64_e32 v[66:67], v[18:19]
	v_mov_b64_e32 v[58:59], v[18:19]
	v_mov_b64_e32 v[54:55], v[18:19]
	v_mov_b64_e32 v[62:63], v[18:19]
	v_readfirstlane_b32 s38, v178
	v_readfirstlane_b32 s39, v176
	v_readfirstlane_b32 s45, v179
	s_mul_i32 s47, s38, 0x180
	s_mul_i32 s37, s39, 0x180000
	s_add_i32 s47, s47, s37
	s_add_u32 s48, s16, s47
	s_addc_u32 s49, s17, 0
	s_lshl_b32 s38, s38, 21
	s_lshl_b32 s39, s39, 11
	s_add_i32 s38, s38, s39
	s_add_u32 s36, s18, s38
	s_addc_u32 s37, s19, 0
	v_and_b32_e32 v114, 63, v158
	s_lshl_b32 s47, s24, 6
	v_add_u32_e32 v115, s47, v114
	v_mul_u32_u24_e32 v116, 0x147b, v115
	v_lshrrev_b32_e32 v116, 17, v116
	v_mul_u32_u24_e32 v117, 25, v116
	v_sub_u32_e32 v117, v115, v117
	v_min_u32_e32 v117, 23, v117
	v_mul_u32_u24_e32 v116, 0x600, v116
	v_lshl_add_u32 v122, v117, 4, v116
	v_add_u32_e32 v115, 0x200, v115
	v_mul_u32_u24_e32 v116, 0x147b, v115
	v_lshrrev_b32_e32 v116, 17, v116
	v_mul_u32_u24_e32 v117, 25, v116
	v_sub_u32_e32 v117, v115, v117
	v_min_u32_e32 v117, 23, v117
	v_mul_u32_u24_e32 v116, 0x600, v116
	v_lshl_add_u32 v123, v117, 4, v116
	v_add_u32_e32 v115, 0x200, v115
	v_mul_u32_u24_e32 v116, 0x147b, v115
	v_lshrrev_b32_e32 v116, 17, v116
	v_mul_u32_u24_e32 v117, 25, v116
	v_sub_u32_e32 v117, v115, v117
	v_min_u32_e32 v117, 23, v117
	v_mul_u32_u24_e32 v116, 0x600, v116
	v_lshl_add_u32 v124, v117, 4, v116
	v_add_u32_e32 v115, s47, v114
	v_mul_u32_u24_e32 v116, 0x1c72, v115
	v_lshrrev_b32_e32 v116, 16, v116
	v_mul_u32_u24_e32 v117, 9, v116
	v_sub_u32_e32 v117, v115, v117
	v_min_u32_e32 v117, 7, v117
	v_lshlrev_b32_e32 v116, 14, v116
	v_lshl_add_u32 v125, v117, 4, v116
	v_add_u32_e32 v115, 0x200, v115
	v_mul_u32_u24_e32 v116, 0x1c72, v115
	v_lshrrev_b32_e32 v116, 16, v116
	v_mul_u32_u24_e32 v117, 9, v116
	v_sub_u32_e32 v117, v115, v117
	v_min_u32_e32 v117, 7, v117
	v_lshlrev_b32_e32 v116, 14, v116
	v_lshl_add_u32 v126, v117, 4, v116
	s_cmp_eq_u32 s24, 0
	s_cbranch_scc0 .Latt_xv
	v_add_u32_e32 v115, 0x600, v114
	v_mul_u32_u24_e32 v116, 0x147b, v115
	v_lshrrev_b32_e32 v116, 17, v116
	v_mul_u32_u24_e32 v117, 25, v116
	v_sub_u32_e32 v117, v115, v117
	v_min_u32_e32 v117, 23, v117
	v_mul_u32_u24_e32 v116, 0x600, v116
	v_lshl_add_u32 v127, v117, 4, v116
	s_branch .Latt_xdone
.Latt_xv:
	s_min_u32 s47, s24, 2
	s_lshl_b32 s47, s47, 6
	s_addk_i32 s47, 0x3c0
	v_add_u32_e32 v115, s47, v114
	v_mul_u32_u24_e32 v116, 0x1c72, v115
	v_lshrrev_b32_e32 v116, 16, v116
	v_mul_u32_u24_e32 v117, 9, v116
	v_sub_u32_e32 v117, v115, v117
	v_min_u32_e32 v117, 7, v117
	v_lshlrev_b32_e32 v116, 14, v116
	v_lshl_add_u32 v127, v117, 4, v116
.Latt_xdone:
	s_lshl_b32 vcc_lo, s24, 10
	s_add_i32 vcc_lo, vcc_lo, s11
	s_mov_b32 m0, vcc_lo
	s_nop 0
	global_load_lds_dwordx4 v122, s[48:49]
	s_add_i32 m0, m0, 0x2000
	s_nop 0
	global_load_lds_dwordx4 v123, s[48:49]
	s_add_i32 m0, m0, 0x2000
	s_nop 0
	global_load_lds_dwordx4 v124, s[48:49]
	s_cmp_eq_u32 s24, 0
	s_cbranch_scc0 .Latt_p1
	s_add_i32 m0, s11, 0x6000
	s_nop 0
	global_load_lds_dwordx4 v127, s[48:49]
.Latt_p1:
	s_add_u32 s48, s48, 0x18000
	s_addc_u32 s49, s49, 0
	s_add_i32 m0, vcc_lo, 0xac00
	s_nop 0
	global_load_lds_dwordx4 v122, s[48:49]
	s_add_i32 m0, m0, 0x2000
	s_nop 0
	global_load_lds_dwordx4 v123, s[48:49]
	s_add_i32 m0, m0, 0x2000
	s_nop 0
	global_load_lds_dwordx4 v124, s[48:49]
	s_add_i32 m0, vcc_lo, 0x6400
	s_nop 0
	global_load_lds_dwordx4 v125, s[36:37]
	s_add_i32 m0, m0, 0x2000
	s_nop 0
	global_load_lds_dwordx4 v126, s[36:37]
	s_min_u32 vcc_hi, s24, 2
	s_lshl_b32 vcc_hi, vcc_hi, 10
	s_add_i32 vcc_hi, vcc_hi, 0xa000
	s_add_i32 vcc_hi, vcc_hi, s11
	s_add_i32 vcc_lo, s11, 0x10c00
	s_cmp_eq_u32 s24, 0
	s_cselect_b32 m0, vcc_lo, vcc_hi
	s_cselect_b32 s38, s48, s36
	s_cselect_b32 s39, s49, s37
	global_load_lds_dwordx4 v127, s[38:39]
	s_add_u32 s48, s48, 0x18000
	s_addc_u32 s49, s49, 0
	s_add_u32 s36, s36, 0x80
	s_addc_u32 s37, s37, 0
	s_waitcnt vmcnt(6)
	s_mov_b32 s46, 0
	s_mov_b32 s47, 0
	s_branch .LBB0_2237
.LBB0_2236:
	s_add_i32 s38, s46, 2
	s_cmp_lt_i32 s38, s45
	s_cbranch_scc0 .Latt_w0
	s_waitcnt vmcnt(6)
	s_branch .Latt_w1

; #define LAS __attribute__((address_space(3)))
; #define MFMA16(a, b, c) __builtin_amdgcn_mfma_f32_16x16x32_bf16((a), (b), (c), 0, 0, 0)
; #define AT_VLD(dst, db_) { _Pragma("unroll") for (int s2 = 0; s2 < 2; ++s2) { const LAS bf16* vp = Vs + ((db_) * 16 + lc) * 72 + 32 * s2 + 4 * g4; \
;                     const u32x2 v0 = *(const LAS u32x2*)vp, v1 = *(const LAS u32x2*)(vp + 16); const u32x4 vw = (u32x4){v0.x, v0.y, v1.x, v1.y}; dst[s2] = __builtin_bit_cast(bf16x8, vw); } }
; DI void u_attn2(Frame& F, int h, int qb, int sp, int ntile) {
;     ...
;     for (int t = 0; t < ntile; ++t) {
;         const int kt = kt0 + t;
;         __syncthreads();
; #pragma unroll
;         for (int i = 0; i < 3; ++i) { const int p = tid + 512 * i, r = p / 24, cc = p - r * 24; *(LAS u32x4*)(Ks + r * 200 + cc * 8) = kreg[i]; }
; #pragma unroll
;         for (int i = 0; i < 2; ++i) { const int p = tid + 512 * i, r = p >> 3, cc = p & 7; *(LAS u32x4*)(Vs + r * 72 + cc * 8) = vreg[i]; }
;         __syncthreads();
;         if (t + 1 < ntile) AT_LOAD(kt + 1)
;     ...
;             {
;                 bf16x8 vfr[2][2];
;     ...
;                 AT_VLD(vfr[0], 0)
; #pragma unroll
;                 for (int db = 0; db < 8; ++db) {
;                     if (db < 7) AT_VLD(vfr[(db + 1) & 1], db + 1)
; #pragma unroll
;                     for (int s2 = 0; s2 < 2; ++s2)
; #pragma unroll
;                         for (int qq = 0; qq < 2; ++qq) o[db][qq] = MFMA16(vfr[db & 1][s2], pf[qq][s2], o[db][qq]);
;                 }
.Latt_w1:
	s_cmp_eq_u32 s46, s45
	s_cbranch_scc1 .LBB0_2244
	s_add_i32 s46, s46, 1
	s_add_i32 s47, s47, 0xac00
	s_cmp_eq_u32 s47, 0x20400
	s_cselect_b32 s47, 0, s47
.LBB0_2237:
	s_barrier
	s_add_i32 s39, s47, 0xac00
	s_cmp_eq_u32 s39, 0x20400
	s_cselect_b32 s39, 0, s39
	s_add_i32 s38, s39, 0xac00
	s_cmp_eq_u32 s38, 0x20400
	s_cselect_b32 s38, 0, s38
	v_add_u32_e32 v113, s47, v187
	v_add_u32_e32 v110, s38, v188
	v_add_u32_e32 v111, s38, v189
	v_add_u32_e32 v112, s38, v190
	v_mov_b32_e32 v234, 0x42800000
	s_lshl_b32 vcc_lo, s24, 10
	s_add_i32 vcc_lo, vcc_lo, s11
	s_add_i32 vcc_hi, s46, 2
	s_cmp_lt_i32 vcc_hi, s45
	s_cbranch_scc0 .Latt_vonly
	s_add_i32 m0, s38, vcc_lo
	s_nop 0
	global_load_lds_dwordx4 v122, s[48:49]
	s_add_i32 m0, m0, 0x2000
	s_nop 0
	global_load_lds_dwordx4 v123, s[48:49]
	s_add_i32 m0, m0, 0x2000
	s_nop 0
	global_load_lds_dwordx4 v124, s[48:49]
	s_branch .Latt_vjobs
.Latt_vonly:
	s_add_i32 vcc_hi, s46, 1
	s_cmp_lt_i32 vcc_hi, s45
	s_cbranch_scc0 .Latt_noload
.Latt_vjobs:
	s_add_i32 vcc_hi, s39, vcc_lo
	s_add_i32 m0, vcc_hi, 0x6400
	s_nop 0
	global_load_lds_dwordx4 v125, s[36:37]
	s_add_i32 m0, m0, 0x2000
	s_nop 0
	global_load_lds_dwordx4 v126, s[36:37]
	s_min_u32 vcc_hi, s24, 2
	s_lshl_b32 vcc_hi, vcc_hi, 10
	s_add_i32 vcc_hi, vcc_hi, s39
	s_add_i32 vcc_hi, vcc_hi, 0xa000
	s_add_i32 vcc_hi, vcc_hi, s11
	s_add_i32 vcc_lo, s38, 0x6000
	s_add_i32 vcc_lo, vcc_lo, s11
	s_cmp_eq_u32 s24, 0
	s_cselect_b32 m0, vcc_lo, vcc_hi
	s_cselect_b32 s38, s48, s36
	s_cselect_b32 s39, s49, s37
	global_load_lds_dwordx4 v127, s[38:39]
	s_add_u32 s48, s48, 0x18000
	s_addc_u32 s49, s49, 0
	s_add_u32 s36, s36, 0x80
	s_addc_u32 s37, s37, 0
.Latt_noload:
	s_cmp_lt_i32 s24, 4
	s_cbranch_scc0 .Latt_gB
	s_cmp_eq_u32 s46, 0
	s_cbranch_scc1 .Latt_A_qk
	v_add3_u32 v18, s46, v181, -1
	v_cmp_le_i32_e32 vcc, v18, v180
	s_cbranch_vccz .Latt_A_qk
	v_add_u32_e32 v140, 0x6000, v111
	ds_read2_b64 v[146:149], v140 offset0:128 offset1:132
	ds_read2_b64 v[244:247], v140 offset0:136 offset1:140
	v_add_u32_e32 v219, 0x6000, v110
	v_add_u32_e32 v140, 0x6800, v111
	ds_read2_b64 v[220:223], v219 offset0:128 offset1:132
	ds_read2_b64 v[224:227], v219 offset0:136 offset1:140
	s_waitcnt lgkmcnt(3)
	v_mfma_f32_16x16x32_bf16 v[106:109], v[146:149], v[198:201], v[106:109]
	v_mfma_f32_16x16x32_bf16 v[102:105], v[146:149], v[210:213], v[102:105]
	ds_read2_b64 v[146:149], v140 offset0:160 offset1:164
	s_waitcnt lgkmcnt(3)
	v_mfma_f32_16x16x32_bf16 v[106:109], v[244:247], v[192:195], v[106:109]
	v_mfma_f32_16x16x32_bf16 v[102:105], v[244:247], v[142:145], v[102:105]
	ds_read2_b64 v[244:247], v140 offset0:168 offset1:172
	v_add_u32_e32 v140, 0x7000, v111
	s_waitcnt lgkmcnt(1)
	v_mfma_f32_16x16x32_bf16 v[98:101], v[146:149], v[198:201], v[98:101]
	v_mfma_f32_16x16x32_bf16 v[94:97], v[146:149], v[210:213], v[94:97]
	ds_read2_b64 v[146:149], v140 offset0:192 offset1:196
	s_waitcnt lgkmcnt(1)
	v_mfma_f32_16x16x32_bf16 v[98:101], v[244:247], v[192:195], v[98:101]
	v_mfma_f32_16x16x32_bf16 v[94:97], v[244:247], v[142:145], v[94:97]
	ds_read2_b64 v[244:247], v140 offset0:200 offset1:204
	v_add_u32_e32 v140, 0x8800, v112
	s_waitcnt lgkmcnt(1)
	v_mfma_f32_16x16x32_bf16 v[90:93], v[146:149], v[198:201], v[90:93]
	v_mfma_f32_16x16x32_bf16 v[86:89], v[146:149], v[210:213], v[86:89]
	ds_read2_b64 v[146:149], v140 offset1:4
	s_waitcnt lgkmcnt(1)
	v_mfma_f32_16x16x32_bf16 v[90:93], v[244:247], v[192:195], v[90:93]
	v_mfma_f32_16x16x32_bf16 v[86:89], v[244:247], v[142:145], v[86:89]
	ds_read2_b64 v[244:247], v140 offset0:8 offset1:12
	v_add_u32_e32 v140, 0x9000, v112
	s_waitcnt lgkmcnt(1)
	v_mfma_f32_16x16x32_bf16 v[82:85], v[146:149], v[198:201], v[82:85]
	v_mfma_f32_16x16x32_bf16 v[78:81], v[146:149], v[210:213], v[78:81]
	ds_read2_b64 v[146:149], v140 offset0:32 offset1:36
	s_waitcnt lgkmcnt(1)
	v_mfma_f32_16x16x32_bf16 v[82:85], v[244:247], v[192:195], v[82:85]
	v_mfma_f32_16x16x32_bf16 v[78:81], v[244:247], v[142:145], v[78:81]
	ds_read2_b64 v[244:247], v140 offset0:40 offset1:44
	v_add_u32_e32 v140, 0x9800, v112
	s_waitcnt lgkmcnt(1)
	v_mfma_f32_16x16x32_bf16 v[70:73], v[146:149], v[198:201], v[70:73]
	v_mfma_f32_16x16x32_bf16 v[74:77], v[146:149], v[210:213], v[74:77]
	ds_read2_b64 v[146:149], v140 offset0:64 offset1:68
	s_waitcnt lgkmcnt(1)
	v_mfma_f32_16x16x32_bf16 v[70:73], v[244:247], v[192:195], v[70:73]
	v_mfma_f32_16x16x32_bf16 v[74:77], v[244:247], v[142:145], v[74:77]
	ds_read2_b64 v[244:247], v140 offset0:72 offset1:76
	v_add_u32_e32 v140, 0xa000, v112
	s_waitcnt lgkmcnt(1)
	v_mfma_f32_16x16x32_bf16 v[66:69], v[146:149], v[198:201], v[66:69]
	v_mfma_f32_16x16x32_bf16 v[58:61], v[146:149], v[210:213], v[58:61]
	ds_read2_b64 v[146:149], v140 offset0:96 offset1:100
	ds_read2_b64 v[150:153], v140 offset0:104 offset1:108
	s_waitcnt lgkmcnt(2)
	v_mfma_f32_16x16x32_bf16 v[66:69], v[244:247], v[192:195], v[66:69]
	v_mfma_f32_16x16x32_bf16 v[58:61], v[244:247], v[142:145], v[58:61]
	v_mfma_f32_16x16x32_bf16 v[134:137], v[220:223], v[198:201], v[134:137]
	v_mfma_f32_16x16x32_bf16 v[118:121], v[220:223], v[210:213], v[118:121]
	s_waitcnt lgkmcnt(1)
	v_mfma_f32_16x16x32_bf16 v[54:57], v[146:149], v[198:201], v[54:57]
	v_mfma_f32_16x16x32_bf16 v[62:65], v[146:149], v[210:213], v[62:65]
	v_mfma_f32_16x16x32_bf16 v[134:137], v[224:227], v[192:195], v[134:137]
	v_mfma_f32_16x16x32_bf16 v[118:121], v[224:227], v[142:145], v[118:121]
	s_waitcnt lgkmcnt(0)
	v_mfma_f32_16x16x32_bf16 v[54:57], v[150:153], v[192:195], v[54:57]
	v_mfma_f32_16x16x32_bf16 v[62:65], v[150:153], v[142:145], v[62:65]
; #define MFMA16(a, b, c) __builtin_amdgcn_mfma_f32_16x16x32_bf16((a), (b), (c), 0, 0, 0)
; DI void u_attn2(Frame& F, int h, int qb, int sp, int ntile) {
;     ...
;             {
;                 bf16x8 kfr[2][4];
; #pragma unroll
;                 for (int kb = 0; kb < 4; ++kb) kfr[0][kb] = ldfrag(Ks, 200, kb * 16, 0, lane);
; #pragma unroll
;                 for (int ks = 0; ks < 6; ++ks) {
;                     if (ks < 5) {
; #pragma unroll
;                         for (int kb = 0; kb < 4; ++kb) kfr[(ks + 1) & 1][kb] = ldfrag(Ks, 200, kb * 16, (ks + 1) * 32, lane); }
; #pragma unroll
;                     for (int kb = 0; kb < 4; ++kb)
; #pragma unroll
;                         for (int qq = 0; qq < 2; ++qq) s[kb][qq] = MFMA16(kfr[ks & 1][kb], qf[qq][ks], s[kb][qq]);
;                 }
;             }
.Latt_A_qk:
	v_cmp_lt_i32_e32 vcc, s46, v179
	s_cbranch_vccz .LBB0_2236
	v_add_u32_e32 v18, s46, v181
	v_cmp_le_i32_e32 vcc, v18, v180
	s_cbranch_vccz .LBB0_2236
	ds_read_b128 v[138:141], v113
	ds_read_b128 v[142:145], v113 offset:6400
	ds_read_b128 v[146:149], v113 offset:12800
	ds_read_b128 v[150:153], v113 offset:19200
	ds_read_b128 v[154:157], v113 offset:64
	ds_read_b128 v[192:195], v113 offset:6464
	ds_read_b128 v[210:213], v113 offset:12864
	ds_read_b128 v[214:217], v113 offset:19264
	s_waitcnt lgkmcnt(7)
	v_mfma_f32_16x16x32_bf16 v[218:221], v[138:141], v[2:5], 0
	ds_read_b128 v[244:247], v113 offset:128
	ds_read_b128 v[248:251], v113 offset:6528
	ds_read_b128 v[198:201], v113 offset:12928
	ds_read_b128 v[230:233], v113 offset:19328
	v_mov_b32_e32 v234, 0x42800000
	v_mfma_f32_16x16x32_bf16 v[138:141], v[138:141], v[30:33], 0
	s_waitcnt lgkmcnt(10)
	v_mfma_f32_16x16x32_bf16 v[222:225], v[142:145], v[2:5], 0
	v_mfma_f32_16x16x32_bf16 v[142:145], v[142:145], v[30:33], 0
	s_waitcnt lgkmcnt(9)
	v_mfma_f32_16x16x32_bf16 v[226:229], v[146:149], v[2:5], 0
	s_waitcnt lgkmcnt(7)
	v_mfma_f32_16x16x32_bf16 v[218:221], v[154:157], v[6:9], v[218:221]
	v_mfma_f32_16x16x32_bf16 v[146:149], v[146:149], v[30:33], 0
	v_mfma_f32_16x16x32_bf16 v[240:243], v[150:153], v[2:5], 0
	v_mfma_f32_16x16x32_bf16 v[150:153], v[150:153], v[30:33], 0
	v_mfma_f32_16x16x32_bf16 v[138:141], v[154:157], v[34:37], v[138:141]
	s_waitcnt lgkmcnt(6)
	v_mfma_f32_16x16x32_bf16 v[154:157], v[192:195], v[6:9], v[222:225]
	v_mfma_f32_16x16x32_bf16 v[142:145], v[192:195], v[34:37], v[142:145]
	s_waitcnt lgkmcnt(5)
	v_mfma_f32_16x16x32_bf16 v[192:195], v[210:213], v[6:9], v[226:229]
	s_waitcnt lgkmcnt(3)
	v_mfma_f32_16x16x32_bf16 v[218:221], v[244:247], v[10:13], v[218:221]
	v_mfma_f32_16x16x32_bf16 v[146:149], v[210:213], v[34:37], v[146:149]
	v_mfma_f32_16x16x32_bf16 v[210:213], v[214:217], v[6:9], v[240:243]
	v_mfma_f32_16x16x32_bf16 v[150:153], v[214:217], v[34:37], v[150:153]
	ds_read_b128 v[214:217], v113 offset:192
	ds_read_b128 v[222:225], v113 offset:6592
	ds_read_b128 v[226:229], v113 offset:12992
	ds_read_b128 v[240:243], v113 offset:19392
	v_mfma_f32_16x16x32_bf16 v[138:141], v[244:247], v[38:41], v[138:141]
	s_waitcnt lgkmcnt(6)
	v_mfma_f32_16x16x32_bf16 v[154:157], v[248:251], v[10:13], v[154:157]
	v_mfma_f32_16x16x32_bf16 v[142:145], v[248:251], v[38:41], v[142:145]
	s_waitcnt lgkmcnt(5)
	v_mfma_f32_16x16x32_bf16 v[192:195], v[198:201], v[10:13], v[192:195]
	s_waitcnt lgkmcnt(3)
	v_mfma_f32_16x16x32_bf16 v[218:221], v[214:217], v[14:17], v[218:221]
	v_mfma_f32_16x16x32_bf16 v[146:149], v[198:201], v[38:41], v[146:149]
	v_mfma_f32_16x16x32_bf16 v[198:201], v[230:233], v[10:13], v[210:213]
	v_mfma_f32_16x16x32_bf16 v[150:153], v[230:233], v[38:41], v[150:153]
	s_nop 1
	ds_read_b128 v[210:213], v113 offset:256
	ds_read_b128 v[230:233], v113 offset:6656
	ds_read_b128 v[244:247], v113 offset:13056
	ds_read_b128 v[248:251], v113 offset:19456
	v_mfma_f32_16x16x32_bf16 v[138:141], v[214:217], v[42:45], v[138:141]
	s_waitcnt lgkmcnt(6)
	v_mfma_f32_16x16x32_bf16 v[154:157], v[222:225], v[14:17], v[154:157]
	v_mfma_f32_16x16x32_bf16 v[142:145], v[222:225], v[42:45], v[142:145]
	s_waitcnt lgkmcnt(5)
	v_mfma_f32_16x16x32_bf16 v[192:195], v[226:229], v[14:17], v[192:195]
	s_waitcnt lgkmcnt(3)
	v_mfma_f32_16x16x32_bf16 v[218:221], v[210:213], v[22:25], v[218:221]
	v_mfma_f32_16x16x32_bf16 v[198:201], v[240:243], v[14:17], v[198:201]
	v_mfma_f32_16x16x32_bf16 v[150:153], v[240:243], v[42:45], v[150:153]
	v_mfma_f32_16x16x32_bf16 v[138:141], v[210:213], v[46:49], v[138:141]
	s_waitcnt lgkmcnt(2)
	v_mfma_f32_16x16x32_bf16 v[154:157], v[230:233], v[22:25], v[154:157]
	v_mfma_f32_16x16x32_bf16 v[146:149], v[226:229], v[42:45], v[146:149]
	ds_read_b128 v[214:217], v113 offset:320
	ds_read_b128 v[222:225], v113 offset:6720
	ds_read_b128 v[226:229], v113 offset:13120
	ds_read_b128 v[240:243], v113 offset:19520
	v_mfma_f32_16x16x32_bf16 v[142:145], v[230:233], v[46:49], v[142:145]
	s_waitcnt lgkmcnt(5)
	v_mfma_f32_16x16x32_bf16 v[192:195], v[244:247], v[22:25], v[192:195]
	s_waitcnt lgkmcnt(3)
; DI float xr16_max(float x) { float a = x, b = x; XR_SWAP("v_permlane16_swap_b32", a, b); return fmaxf(a, b); }
; DI float xr32_max(float x) { float a = x, b = x; XR_SWAP("v_permlane32_swap_b32", a, b); return fmaxf(a, b); }
; DI float xr16_sum(float x) { float a = x, b = x; XR_SWAP("v_permlane16_swap_b32", a, b); return a + b; }
; DI float xr32_sum(float x) { float a = x, b = x; XR_SWAP("v_permlane32_swap_b32", a, b); return a + b; }
; DI void u_attn2(Frame& F, int h, int qb, int sp, int ntile) {
;     ...
;             bf16x8 pf[2][2];
; #pragma unroll
;             for (int qq = 0; qq < 2; ++qq) {
;                 float mx = -1e30f;
; #pragma unroll
;                 for (int kb = 0; kb < 4; ++kb) mx = fmaxf(mx, fmaxf(fmaxf(s[kb][qq][0], s[kb][qq][1]), fmaxf(s[kb][qq][2], s[kb][qq][3])));
;                 mx = xr32_max(xr16_max(mx));
;                 const float mn = fmaxf(mrun[qq], mx), alpha = __builtin_amdgcn_exp2f(mrun[qq] - mn); mrun[qq] = mn;
;                 float ps = 0.f; float p[16];
; #pragma unroll
;                 for (int kb = 0; kb < 4; ++kb)
; #pragma unroll
;                     for (int r = 0; r < 4; ++r) { p[kb * 4 + r] = __builtin_amdgcn_exp2f(s[kb][qq][r] - mn); ps += p[kb * 4 + r]; }
;                 ps = xr32_sum(xr16_sum(ps));
;                 lrun[qq] = lrun[qq] * alpha + ps;
; if (__builtin_amdgcn_ballot_w64(alpha != 1.0f) != 0ull) {
; #pragma unroll
;                     for (int db = 0; db < 8; ++db) o[db][qq] = o[db][qq] * alpha; }
	v_mfma_f32_16x16x32_bf16 v[218:221], v[214:217], v[26:29], v[218:221]
	v_mfma_f32_16x16x32_bf16 v[198:201], v[248:251], v[22:25], v[198:201]
	v_mfma_f32_16x16x32_bf16 v[230:233], v[248:251], v[46:49], v[150:153]
	v_mfma_f32_16x16x32_bf16 v[150:153], v[214:217], v[50:53], v[138:141]
	s_waitcnt lgkmcnt(2)
	v_mfma_f32_16x16x32_bf16 v[214:217], v[222:225], v[26:29], v[154:157]
	v_mfma_f32_16x16x32_bf16 v[210:213], v[244:247], v[46:49], v[146:149]
	v_mfma_f32_16x16x32_bf16 v[146:149], v[222:225], v[50:53], v[142:145]
	s_waitcnt lgkmcnt(1)
	v_mfma_f32_16x16x32_bf16 v[222:225], v[226:229], v[26:29], v[192:195]
	s_waitcnt lgkmcnt(0)
	v_mfma_f32_16x16x32_bf16 v[154:157], v[240:243], v[26:29], v[198:201]
	v_mfma_f32_16x16x32_bf16 v[138:141], v[240:243], v[50:53], v[230:233]
	s_nop 1
	v_mfma_f32_16x16x32_bf16 v[142:145], v[226:229], v[50:53], v[210:213]
	s_nop 7
	s_nop 1
	v_max_f32_e32 v18, v220, v221
	v_max3_f32 v18, v218, v219, v18
	v_max_f32_e32 v20, v216, v217
	v_max3_f32 v20, v214, v215, v20
	v_max3_f32 v18, v18, s1, v20
	v_max_f32_e32 v20, v224, v225
	v_max_f32_e32 v21, v156, v157
	v_max3_f32 v20, v222, v223, v20
	v_max3_f32 v21, v154, v155, v21
	v_max3_f32 v18, v18, v20, v21
	v_mov_b32_e32 v20, v18
	s_nop 1
	v_permlane16_swap_b32 v18, v20
	s_nop 0
	v_max_f32_e32 v18, v18, v20
	v_mov_b32_e32 v20, v18
	s_nop 1
	v_permlane32_swap_b32 v18, v20
	s_nop 0
	v_max3_f32 v21, v164, v18, v20
	v_sub_f32_e32 v20, v218, v21
	v_sub_f32_e32 v18, v164, v21
	v_exp_f32_e32 v192, v20
	v_sub_f32_e32 v164, v219, v21
	v_exp_f32_e32 v194, v164
	v_sub_f32_e32 v164, v220, v21
	v_exp_f32_e32 v164, v164
	v_sub_f32_e32 v191, v221, v21
	v_exp_f32_e32 v191, v191
	v_sub_f32_e32 v193, v214, v21
	v_add_f32_e32 v20, 0, v192
	v_exp_f32_e32 v193, v193
	v_sub_f32_e32 v195, v215, v21
	v_add_f32_e32 v20, v194, v20
	v_exp_f32_e32 v195, v195
	v_sub_f32_e32 v198, v216, v21
	v_add_f32_e32 v20, v164, v20
	v_exp_f32_e32 v203, v198
	v_sub_f32_e32 v198, v217, v21
	v_add_f32_e32 v20, v191, v20
	v_exp_f32_e32 v210, v198
	v_sub_f32_e32 v198, v222, v21
	v_add_f32_e32 v20, v193, v20
	v_exp_f32_e32 v211, v198
	v_sub_f32_e32 v198, v223, v21
	v_add_f32_e32 v20, v195, v20
	v_exp_f32_e32 v212, v198
	v_sub_f32_e32 v198, v224, v21
	v_add_f32_e32 v20, v203, v20
	v_exp_f32_e32 v213, v198
	v_sub_f32_e32 v198, v225, v21
	v_add_f32_e32 v20, v210, v20
	v_exp_f32_e32 v214, v198
	v_sub_f32_e32 v154, v154, v21
	v_add_f32_e32 v20, v211, v20
	v_exp_f32_e32 v215, v154
	v_sub_f32_e32 v154, v155, v21
	v_add_f32_e32 v20, v212, v20
	v_exp_f32_e32 v217, v154
	v_sub_f32_e32 v154, v156, v21
	v_add_f32_e32 v20, v213, v20
	v_exp_f32_e32 v156, v154
	v_sub_f32_e32 v154, v157, v21
	v_add_f32_e32 v20, v214, v20
	v_exp_f32_e32 v157, v154
	v_add_f32_e32 v20, v215, v20
	v_add_f32_e32 v20, v217, v20
	v_add_f32_e32 v20, v156, v20
	v_add_f32_e32 v20, v157, v20
	v_exp_f32_e32 v18, v18
	v_mov_b32_e32 v154, v20
	s_nop 1
	v_permlane16_swap_b32 v20, v154
	v_cmp_neq_f32_e32 vcc, 1.0, v18
	v_add_f32_e32 v154, v20, v154
	v_mov_b32_e32 v155, v154
	s_nop 1
	v_permlane32_swap_b32 v154, v155
	s_cbranch_vccz .Latt_r0_A
	v_pk_mul_f32 v[136:137], v[136:137], v[18:19] op_sel_hi:[1,0]
	v_pk_mul_f32 v[134:135], v[134:135], v[18:19] op_sel_hi:[1,0]
	v_pk_mul_f32 v[108:109], v[108:109], v[18:19] op_sel_hi:[1,0]
	v_pk_mul_f32 v[106:107], v[106:107], v[18:19] op_sel_hi:[1,0]
	v_pk_mul_f32 v[100:101], v[100:101], v[18:19] op_sel_hi:[1,0]
	v_pk_mul_f32 v[98:99], v[98:99], v[18:19] op_sel_hi:[1,0]
	v_pk_mul_f32 v[92:93], v[92:93], v[18:19] op_sel_hi:[1,0]
	v_pk_mul_f32 v[90:91], v[90:91], v[18:19] op_sel_hi:[1,0]
	v_pk_mul_f32 v[84:85], v[84:85], v[18:19] op_sel_hi:[1,0]
	v_pk_mul_f32 v[82:83], v[82:83], v[18:19] op_sel_hi:[1,0]
	v_pk_mul_f32 v[72:73], v[72:73], v[18:19] op_sel_hi:[1,0]
	v_pk_mul_f32 v[70:71], v[70:71], v[18:19] op_sel_hi:[1,0]
	v_pk_mul_f32 v[68:69], v[68:69], v[18:19] op_sel_hi:[1,0]
	v_pk_mul_f32 v[66:67], v[66:67], v[18:19] op_sel_hi:[1,0]
	v_pk_mul_f32 v[56:57], v[56:57], v[18:19] op_sel_hi:[1,0]
	v_pk_mul_f32 v[54:55], v[54:55], v[18:19] op_sel_hi:[1,0]

; DI unsigned pk2(float lo, float hi) { const f32x2 v = {lo, hi}; const bf16x2_t b = __builtin_convertvector(v, bf16x2_t); return __builtin_bit_cast(unsigned, b); }
; DI float xr16_sum(float x) { float a = x, b = x; XR_SWAP("v_permlane16_swap_b32", a, b); return a + b; }
; DI float xr32_sum(float x) { float a = x, b = x; XR_SWAP("v_permlane32_swap_b32", a, b); return a + b; }
; #define MFMA16(a, b, c) __builtin_amdgcn_mfma_f32_16x16x32_bf16((a), (b), (c), 0, 0, 0)
; #define AT_VLD(dst, db_) { _Pragma("unroll") for (int s2 = 0; s2 < 2; ++s2) { const LAS bf16* vp = Vs + ((db_) * 16 + lc) * 72 + 32 * s2 + 4 * g4; \
;                     const u32x2 v0 = *(const LAS u32x2*)vp, v1 = *(const LAS u32x2*)(vp + 16); const u32x4 vw = (u32x4){v0.x, v0.y, v1.x, v1.y}; dst[s2] = __builtin_bit_cast(bf16x8, vw); } }
; DI void u_attn2(Frame& F, int h, int qb, int sp, int ntile) {
;     ...
;                 ps = xr32_sum(xr16_sum(ps));
;                 lrun[qq] = lrun[qq] * alpha + ps;
; if (__builtin_amdgcn_ballot_w64(alpha != 1.0f) != 0ull) {
; #pragma unroll
;                     for (int db = 0; db < 8; ++db) o[db][qq] = o[db][qq] * alpha; }
; #pragma unroll
;                 for (int s2 = 0; s2 < 2; ++s2) { u32x4 pw; pw.x = pk2(p[8 * s2], p[8 * s2 + 1]); pw.y = pk2(p[8 * s2 + 2], p[8 * s2 + 3]); pw.z = pk2(p[8 * s2 + 4], p[8 * s2 + 5]); pw.w = pk2(p[8 * s2 + 6], p[8 * s2 + 7]); pf[qq][s2] = __builtin_bit_cast(bf16x8, pw); }
;             }
;             {
;                 bf16x8 vfr[2][2];
;     ...
;                 AT_VLD(vfr[0], 0)
; #pragma unroll
;                 for (int db = 0; db < 8; ++db) {
;                     if (db < 7) AT_VLD(vfr[(db + 1) & 1], db + 1)
; #pragma unroll
;                     for (int s2 = 0; s2 < 2; ++s2)
; #pragma unroll
;                         for (int qq = 0; qq < 2; ++qq) o[db][qq] = MFMA16(vfr[db & 1][s2], pf[qq][s2], o[db][qq]);
;                 }
.Latt_r1_B:
	v_cvt_pk_bf16_f32 v142, v142, v143
	v_cvt_pk_bf16_f32 v143, v144, v145
	v_cvt_pk_bf16_f32 v145, v140, v141
	v_cvt_pk_bf16_f32 v198, v192, v194
	v_cvt_pk_bf16_f32 v200, v193, v195
	v_cvt_pk_bf16_f32 v192, v211, v212
	v_cvt_pk_bf16_f32 v193, v213, v214
	v_cvt_pk_bf16_f32 v212, v146, v147
	v_cvt_pk_bf16_f32 v213, v148, v149
	v_cvt_pk_bf16_f32 v199, v164, v191
	v_cvt_pk_bf16_f32 v201, v203, v210
	v_cvt_pk_bf16_f32 v210, v162, v218
	v_cvt_pk_bf16_f32 v211, v150, v151
	v_cvt_pk_bf16_f32 v194, v215, v217
	v_cvt_pk_bf16_f32 v195, v156, v157
	v_cvt_pk_bf16_f32 v144, v152, v153
	v_add_f32_e32 v138, v138, v139
	v_fmac_f32_e32 v138, v163, v20
	v_add_f32_e32 v20, v154, v155
	v_fmac_f32_e32 v20, v165, v18
	v_mov_b32_e32 v165, v20
	v_mov_b32_e32 v163, v138
	v_mov_b32_e32 v164, v21
	v_mov_b32_e32 v162, v216
	v_add_u32_e32 v140, 0x6000, v111
	ds_read2_b64 v[146:149], v140 offset0:128 offset1:132
	ds_read2_b64 v[244:247], v140 offset0:136 offset1:140
	v_add_u32_e32 v219, 0x6000, v110
	v_add_u32_e32 v140, 0x6800, v111
	ds_read2_b64 v[220:223], v219 offset0:128 offset1:132
	ds_read2_b64 v[224:227], v219 offset0:136 offset1:140
	s_waitcnt lgkmcnt(3)
	v_mfma_f32_16x16x32_bf16 v[106:109], v[146:149], v[198:201], v[106:109]
	v_mfma_f32_16x16x32_bf16 v[102:105], v[146:149], v[210:213], v[102:105]
	ds_read2_b64 v[146:149], v140 offset0:160 offset1:164
	s_waitcnt lgkmcnt(3)
	v_mfma_f32_16x16x32_bf16 v[106:109], v[244:247], v[192:195], v[106:109]
	v_mfma_f32_16x16x32_bf16 v[102:105], v[244:247], v[142:145], v[102:105]
	ds_read2_b64 v[244:247], v140 offset0:168 offset1:172
	v_add_u32_e32 v140, 0x7000, v111
	s_waitcnt lgkmcnt(1)
	v_mfma_f32_16x16x32_bf16 v[98:101], v[146:149], v[198:201], v[98:101]
	v_mfma_f32_16x16x32_bf16 v[94:97], v[146:149], v[210:213], v[94:97]
	ds_read2_b64 v[146:149], v140 offset0:192 offset1:196
	s_waitcnt lgkmcnt(1)
	v_mfma_f32_16x16x32_bf16 v[98:101], v[244:247], v[192:195], v[98:101]
	v_mfma_f32_16x16x32_bf16 v[94:97], v[244:247], v[142:145], v[94:97]
	ds_read2_b64 v[244:247], v140 offset0:200 offset1:204
	v_add_u32_e32 v140, 0x8800, v112
	s_waitcnt lgkmcnt(1)
	v_mfma_f32_16x16x32_bf16 v[90:93], v[146:149], v[198:201], v[90:93]
	v_mfma_f32_16x16x32_bf16 v[86:89], v[146:149], v[210:213], v[86:89]
	ds_read2_b64 v[146:149], v140 offset1:4
	s_waitcnt lgkmcnt(1)
	v_mfma_f32_16x16x32_bf16 v[90:93], v[244:247], v[192:195], v[90:93]
	v_mfma_f32_16x16x32_bf16 v[86:89], v[244:247], v[142:145], v[86:89]
	ds_read2_b64 v[244:247], v140 offset0:8 offset1:12
	v_add_u32_e32 v140, 0x9000, v112
	s_waitcnt lgkmcnt(1)
	v_mfma_f32_16x16x32_bf16 v[82:85], v[146:149], v[198:201], v[82:85]
	v_mfma_f32_16x16x32_bf16 v[78:81], v[146:149], v[210:213], v[78:81]
	ds_read2_b64 v[146:149], v140 offset0:32 offset1:36
	s_waitcnt lgkmcnt(1)
	v_mfma_f32_16x16x32_bf16 v[82:85], v[244:247], v[192:195], v[82:85]
	v_mfma_f32_16x16x32_bf16 v[78:81], v[244:247], v[142:145], v[78:81]
	ds_read2_b64 v[244:247], v140 offset0:40 offset1:44
	v_add_u32_e32 v140, 0x9800, v112
	s_waitcnt lgkmcnt(1)
	v_mfma_f32_16x16x32_bf16 v[70:73], v[146:149], v[198:201], v[70:73]
	v_mfma_f32_16x16x32_bf16 v[74:77], v[146:149], v[210:213], v[74:77]
	ds_read2_b64 v[146:149], v140 offset0:64 offset1:68
	s_waitcnt lgkmcnt(1)
	v_mfma_f32_16x16x32_bf16 v[70:73], v[244:247], v[192:195], v[70:73]
	v_mfma_f32_16x16x32_bf16 v[74:77], v[244:247], v[142:145], v[74:77]
	ds_read2_b64 v[244:247], v140 offset0:72 offset1:76
	v_add_u32_e32 v140, 0xa000, v112
	s_waitcnt lgkmcnt(1)
	v_mfma_f32_16x16x32_bf16 v[66:69], v[146:149], v[198:201], v[66:69]
	v_mfma_f32_16x16x32_bf16 v[58:61], v[146:149], v[210:213], v[58:61]
	ds_read2_b64 v[146:149], v140 offset0:96 offset1:100
	ds_read2_b64 v[150:153], v140 offset0:104 offset1:108
	s_waitcnt lgkmcnt(2)
	v_mfma_f32_16x16x32_bf16 v[66:69], v[244:247], v[192:195], v[66:69]
	v_mfma_f32_16x16x32_bf16 v[58:61], v[244:247], v[142:145], v[58:61]
	v_mfma_f32_16x16x32_bf16 v[134:137], v[220:223], v[198:201], v[134:137]
	v_mfma_f32_16x16x32_bf16 v[118:121], v[220:223], v[210:213], v[118:121]
	s_waitcnt lgkmcnt(1)
	v_mfma_f32_16x16x32_bf16 v[54:57], v[146:149], v[198:201], v[54:57]
	v_mfma_f32_16x16x32_bf16 v[62:65], v[146:149], v[210:213], v[62:65]
	v_mfma_f32_16x16x32_bf16 v[134:137], v[224:227], v[192:195], v[134:137]
	v_mfma_f32_16x16x32_bf16 v[118:121], v[224:227], v[142:145], v[118:121]
	s_waitcnt lgkmcnt(0)
	v_mfma_f32_16x16x32_bf16 v[54:57], v[150:153], v[192:195], v[54:57]
	v_mfma_f32_16x16x32_bf16 v[62:65], v[150:153], v[142:145], v[62:65]
; #define MFMA16(a, b, c) __builtin_amdgcn_mfma_f32_16x16x32_bf16((a), (b), (c), 0, 0, 0)
; DI void u_attn2(Frame& F, int h, int qb, int sp, int ntile) {
;     ...
;             {
;                 bf16x8 kfr[2][4];
; #pragma unroll
;                 for (int kb = 0; kb < 4; ++kb) kfr[0][kb] = ldfrag(Ks, 200, kb * 16, 0, lane);
; #pragma unroll
;                 for (int ks = 0; ks < 6; ++ks) {
;                     if (ks < 5) {
; #pragma unroll
;                         for (int kb = 0; kb < 4; ++kb) kfr[(ks + 1) & 1][kb] = ldfrag(Ks, 200, kb * 16, (ks + 1) * 32, lane); }
; #pragma unroll
;                     for (int kb = 0; kb < 4; ++kb)
; #pragma unroll
;                         for (int qq = 0; qq < 2; ++qq) s[kb][qq] = MFMA16(kfr[ks & 1][kb], qf[qq][ks], s[kb][qq]);
;                 }
;             }
.Latt_B_qk:
	v_cmp_lt_i32_e32 vcc, s46, v179
	s_cbranch_vccz .LBB0_2236
	v_add_u32_e32 v18, s46, v181
	v_cmp_le_i32_e32 vcc, v18, v180
	s_cbranch_vccz .LBB0_2236
	ds_read_b128 v[138:141], v113
	ds_read_b128 v[142:145], v113 offset:6400
	ds_read_b128 v[146:149], v113 offset:12800
	ds_read_b128 v[150:153], v113 offset:19200
	ds_read_b128 v[154:157], v113 offset:64
	ds_read_b128 v[192:195], v113 offset:6464
	ds_read_b128 v[210:213], v113 offset:12864
	ds_read_b128 v[214:217], v113 offset:19264
	s_waitcnt lgkmcnt(7)
	v_mfma_f32_16x16x32_bf16 v[218:221], v[138:141], v[2:5], 0
	ds_read_b128 v[244:247], v113 offset:128
	ds_read_b128 v[248:251], v113 offset:6528
	ds_read_b128 v[198:201], v113 offset:12928
	ds_read_b128 v[230:233], v113 offset:19328
	v_mov_b32_e32 v234, 0x42800000
	v_mfma_f32_16x16x32_bf16 v[138:141], v[138:141], v[30:33], 0
	s_waitcnt lgkmcnt(10)
	v_mfma_f32_16x16x32_bf16 v[222:225], v[142:145], v[2:5], 0
	v_mfma_f32_16x16x32_bf16 v[142:145], v[142:145], v[30:33], 0
	s_waitcnt lgkmcnt(9)
	v_mfma_f32_16x16x32_bf16 v[226:229], v[146:149], v[2:5], 0
	s_waitcnt lgkmcnt(7)
	v_mfma_f32_16x16x32_bf16 v[218:221], v[154:157], v[6:9], v[218:221]
	v_mfma_f32_16x16x32_bf16 v[146:149], v[146:149], v[30:33], 0
	v_mfma_f32_16x16x32_bf16 v[240:243], v[150:153], v[2:5], 0
	v_mfma_f32_16x16x32_bf16 v[150:153], v[150:153], v[30:33], 0
	v_mfma_f32_16x16x32_bf16 v[138:141], v[154:157], v[34:37], v[138:141]
	s_waitcnt lgkmcnt(6)
	v_mfma_f32_16x16x32_bf16 v[154:157], v[192:195], v[6:9], v[222:225]
	v_mfma_f32_16x16x32_bf16 v[142:145], v[192:195], v[34:37], v[142:145]
	s_waitcnt lgkmcnt(5)
	v_mfma_f32_16x16x32_bf16 v[192:195], v[210:213], v[6:9], v[226:229]
	s_waitcnt lgkmcnt(3)
	v_mfma_f32_16x16x32_bf16 v[218:221], v[244:247], v[10:13], v[218:221]
	v_mfma_f32_16x16x32_bf16 v[146:149], v[210:213], v[34:37], v[146:149]
	v_mfma_f32_16x16x32_bf16 v[210:213], v[214:217], v[6:9], v[240:243]
	v_mfma_f32_16x16x32_bf16 v[150:153], v[214:217], v[34:37], v[150:153]
	ds_read_b128 v[214:217], v113 offset:192
	ds_read_b128 v[222:225], v113 offset:6592
	ds_read_b128 v[226:229], v113 offset:12992
	ds_read_b128 v[240:243], v113 offset:19392
	v_mfma_f32_16x16x32_bf16 v[138:141], v[244:247], v[38:41], v[138:141]
	s_waitcnt lgkmcnt(6)
	v_mfma_f32_16x16x32_bf16 v[154:157], v[248:251], v[10:13], v[154:157]
	v_mfma_f32_16x16x32_bf16 v[142:145], v[248:251], v[38:41], v[142:145]
	s_waitcnt lgkmcnt(5)
	v_mfma_f32_16x16x32_bf16 v[192:195], v[198:201], v[10:13], v[192:195]
	s_waitcnt lgkmcnt(3)
	v_mfma_f32_16x16x32_bf16 v[218:221], v[214:217], v[14:17], v[218:221]
	v_mfma_f32_16x16x32_bf16 v[146:149], v[198:201], v[38:41], v[146:149]
	v_mfma_f32_16x16x32_bf16 v[198:201], v[230:233], v[10:13], v[210:213]
	v_mfma_f32_16x16x32_bf16 v[150:153], v[230:233], v[38:41], v[150:153]
	s_nop 1
	ds_read_b128 v[210:213], v113 offset:256
	ds_read_b128 v[230:233], v113 offset:6656
	ds_read_b128 v[244:247], v113 offset:13056
	ds_read_b128 v[248:251], v113 offset:19456
	v_mfma_f32_16x16x32_bf16 v[138:141], v[214:217], v[42:45], v[138:141]
	s_waitcnt lgkmcnt(6)
	v_mfma_f32_16x16x32_bf16 v[154:157], v[222:225], v[14:17], v[154:157]
	v_mfma_f32_16x16x32_bf16 v[142:145], v[222:225], v[42:45], v[142:145]
	s_waitcnt lgkmcnt(5)
	v_mfma_f32_16x16x32_bf16 v[192:195], v[226:229], v[14:17], v[192:195]
	s_waitcnt lgkmcnt(3)
	v_mfma_f32_16x16x32_bf16 v[218:221], v[210:213], v[22:25], v[218:221]
	v_mfma_f32_16x16x32_bf16 v[198:201], v[240:243], v[14:17], v[198:201]
	v_mfma_f32_16x16x32_bf16 v[150:153], v[240:243], v[42:45], v[150:153]
	v_mfma_f32_16x16x32_bf16 v[138:141], v[210:213], v[46:49], v[138:141]
	s_waitcnt lgkmcnt(2)
	v_mfma_f32_16x16x32_bf16 v[154:157], v[230:233], v[22:25], v[154:157]
	v_mfma_f32_16x16x32_bf16 v[146:149], v[226:229], v[42:45], v[146:149]
	ds_read_b128 v[214:217], v113 offset:320
	ds_read_b128 v[222:225], v113 offset:6720
	ds_read_b128 v[226:229], v113 offset:13120
	ds_read_b128 v[240:243], v113 offset:19520
	v_mfma_f32_16x16x32_bf16 v[142:145], v[230:233], v[46:49], v[142:145]
	s_waitcnt lgkmcnt(5)
	v_mfma_f32_16x16x32_bf16 v[192:195], v[244:247], v[22:25], v[192:195]
	s_waitcnt lgkmcnt(3)
	v_mfma_f32_16x16x32_bf16 v[218:221], v[214:217], v[26:29], v[218:221]
	v_mfma_f32_16x16x32_bf16 v[198:201], v[248:251], v[22:25], v[198:201]
	v_mfma_f32_16x16x32_bf16 v[230:233], v[248:251], v[46:49], v[150:153]
	v_mfma_f32_16x16x32_bf16 v[150:153], v[214:217], v[50:53], v[138:141]
	s_waitcnt lgkmcnt(2)
	v_mfma_f32_16x16x32_bf16 v[214:217], v[222:225], v[26:29], v[154:157]
	v_mfma_f32_16x16x32_bf16 v[210:213], v[244:247], v[46:49], v[146:149]
	v_mfma_f32_16x16x32_bf16 v[146:149], v[222:225], v[50:53], v[142:145]
	s_waitcnt lgkmcnt(1)
	v_mfma_f32_16x16x32_bf16 v[222:225], v[226:229], v[26:29], v[192:195]
	s_waitcnt lgkmcnt(0)
	v_mfma_f32_16x16x32_bf16 v[154:157], v[240:243], v[26:29], v[198:201]
	v_mfma_f32_16x16x32_bf16 v[138:141], v[240:243], v[50:53], v[230:233]
	s_nop 1
	v_mfma_f32_16x16x32_bf16 v[142:145], v[226:229], v[50:53], v[210:213]
	s_branch .LBB0_2236
; #define GAS __attribute__((address_space(1)))
; DI u32x2 pk4_(const f32x4 v) { u32x2 o; o.x = pk2(v.x, v.y); o.y = pk2(v.z, v.w); return o; }
; DI void u_attn2(Frame& F, int h, int qb, int sp, int ntile) {
;     ...
;     const int slot = att_slot(h, qb, sp);
;     bf16* po = (bf16*)(ws + WS_APO) + (size_t)slot * 32768; float* pm = (float*)(ws + WS_APM) + (size_t)slot * 512;
; #pragma unroll
;     for (int db = 0; db < 8; ++db)
; #pragma unroll
;         for (int qq = 0; qq < 2; ++qq) *(GAS u32x2*)(po + (size_t)(w * 32 + qq * 16 + lc) * 128 + db * 16 + 4 * g4) = pk4_(o[db][qq]);
;     if (g4 == 0) {
; #pragma unroll
;         for (int qq = 0; qq < 2; ++qq) { *(GAS f32x2*)(pm + (w * 32 + qq * 16 + lc) * 2) = (f32x2){mrun[qq], lrun[qq]}; } }
.LBB0_2244:
.LBB0_2245:
	s_or_b64 exec, exec, s[30:31]
	v_lshrrev_b32_e32 v2, 2, v177
	v_add_u32_e32 v4, 1, v2
	v_lshlrev_b32_e32 v2, 1, v2
	v_sub_u32_e32 v2, v177, v2
	v_mul_u32_u24_e32 v3, 0x90, v178
	v_mul_i32_i24_e32 v2, v2, v4
	v_add3_u32 v2, v176, v3, v2
	v_ashrrev_i32_e32 v3, 31, v2
	v_lshlrev_b64 v[4:5], 16, v[2:3]
	v_lshl_add_u64 v[8:9], s[22:23], 0, v[4:5]
	v_or_b32_e32 v4, s42, v161
	v_mov_b32_e32 v161, v19
	v_ashrrev_i32_e32 v5, 31, v4
	v_or_b32_e32 v14, 16, v4
	v_lshl_add_u64 v[8:9], v[8:9], 0, v[160:161]
	v_lshlrev_b64 v[12:13], 8, v[4:5]
	v_ashrrev_i32_e32 v15, 31, v14
	v_cvt_pk_bf16_f32 v10, v134, v135
	v_cvt_pk_bf16_f32 v11, v136, v137
	v_lshl_add_u64 v[12:13], v[8:9], 0, v[12:13]
	v_lshlrev_b64 v[14:15], 8, v[14:15]
	global_store_dwordx2 v[12:13], v[10:11], off
	v_cvt_pk_bf16_f32 v10, v118, v119
	v_cvt_pk_bf16_f32 v11, v120, v121
	v_lshl_add_u64 v[8:9], v[8:9], 0, v[14:15]
	global_store_dwordx2 v[8:9], v[10:11], off
	v_cvt_pk_bf16_f32 v10, v106, v107
	v_cvt_pk_bf16_f32 v11, v108, v109
	global_store_dwordx2 v[12:13], v[10:11], off offset:32
	v_cvt_pk_bf16_f32 v10, v102, v103
	v_cvt_pk_bf16_f32 v11, v104, v105
	global_store_dwordx2 v[8:9], v[10:11], off offset:32
	v_cvt_pk_bf16_f32 v10, v98, v99
	v_cvt_pk_bf16_f32 v11, v100, v101
	global_store_dwordx2 v[12:13], v[10:11], off offset:64
	v_cvt_pk_bf16_f32 v10, v94, v95
	v_cvt_pk_bf16_f32 v11, v96, v97
	global_store_dwordx2 v[8:9], v[10:11], off offset:64
	v_cvt_pk_bf16_f32 v10, v90, v91
	v_cvt_pk_bf16_f32 v11, v92, v93
	global_store_dwordx2 v[12:13], v[10:11], off offset:96
	v_cvt_pk_bf16_f32 v10, v86, v87
	v_cvt_pk_bf16_f32 v11, v88, v89
	global_store_dwordx2 v[8:9], v[10:11], off offset:96
	v_cvt_pk_bf16_f32 v10, v82, v83
	v_cvt_pk_bf16_f32 v11, v84, v85
	global_store_dwordx2 v[12:13], v[10:11], off offset:128
	v_cvt_pk_bf16_f32 v10, v78, v79
	v_cvt_pk_bf16_f32 v11, v80, v81
	global_store_dwordx2 v[8:9], v[10:11], off offset:128
	v_cvt_pk_bf16_f32 v10, v70, v71
	v_cvt_pk_bf16_f32 v11, v72, v73
	global_store_dwordx2 v[12:13], v[10:11], off offset:160
	v_cvt_pk_bf16_f32 v10, v74, v75
	v_cvt_pk_bf16_f32 v11, v76, v77
	global_store_dwordx2 v[8:9], v[10:11], off offset:160
	v_cvt_pk_bf16_f32 v10, v66, v67
	v_cvt_pk_bf16_f32 v11, v68, v69
	global_store_dwordx2 v[12:13], v[10:11], off offset:192
	v_cvt_pk_bf16_f32 v10, v58, v59
	v_cvt_pk_bf16_f32 v11, v60, v61
	v_and_b32_e32 v6, 63, v158
	global_store_dwordx2 v[8:9], v[10:11], off offset:192
	v_cvt_pk_bf16_f32 v10, v54, v55
	v_cvt_pk_bf16_f32 v11, v56, v57
	global_store_dwordx2 v[12:13], v[10:11], off offset:224
	v_cvt_pk_bf16_f32 v10, v62, v63
	v_cvt_pk_bf16_f32 v11, v64, v65
	v_cmp_gt_u32_e32 vcc, 16, v6
	global_store_dwordx2 v[8:9], v[10:11], off offset:224
	s_and_saveexec_b64 s[30:31], vcc
	v_readlane_b32 s46, v235, 30
	v_readlane_b32 s47, v235, 31
	s_cbranch_execz .LBB0_2230
	v_lshlrev_b64 v[2:3], 11, v[2:3]
	v_lshlrev_b32_e32 v4, 1, v4
	v_lshl_add_u64 v[2:3], s[26:27], 0, v[2:3]
	v_ashrrev_i32_e32 v5, 31, v4
	v_lshl_add_u64 v[2:3], v[4:5], 2, v[2:3]
	global_store_dwordx2 v[2:3], v[164:165], off
	global_store_dwordx2 v[2:3], v[162:163], off offset:128
	s_branch .LBB0_2230
